# static s_setprio 1 for waves 4-7 (the younger wave of each SIMD pair) for the whole kernel
# baseline (speedup 1.0000x reference)
_Z14fwd_megakernel6Params:
	s_load_dwordx16 s[68:83], s[0:1], 0x0
	s_load_dwordx16 s[44:59], s[0:1], 0x40
	s_load_dwordx2 s[96:97], s[0:1], 0xb0
	s_load_dwordx4 s[4:7], s[0:1], 0xa0
	s_load_dwordx8 s[84:91], s[0:1], 0x80
	s_add_u32 s92, s0, 0xb8
	s_load_dword s67, s[0:1], 0xb8
	s_addc_u32 s93, s1, 0
	s_waitcnt lgkmcnt(0)
	v_writelane_b32 v255, s4, 0
	v_and_b32_e32 v176, 0x3ff, v0
	v_mov_b32_e32 v1, v176
	v_writelane_b32 v255, s5, 1
	v_writelane_b32 v255, s6, 2
	v_writelane_b32 v255, s7, 3
	s_mov_b64 s[4:5], 0
	s_add_u32 s0, s96, s4
	s_addc_u32 s1, s97, s5
	v_lshrrev_b32_e32 v213, 8, v176
	s_nop 0
	v_readfirstlane_b32 s98, v213
	s_cmp_eq_u32 s98, 0
	s_cbranch_scc1 .Lprio_keep
	s_setprio 1
.Lprio_keep:
	s_cmpk_gt_i32 s2, 0xc3f
	v_and_b32_e32 v2, 63, v1
	s_cbranch_scc1 .LBB0_33
	s_add_u32 s6, s0, 0x1800000
	s_addc_u32 s7, s1, 0
	s_add_u32 s8, s0, 0x1600000
	s_addc_u32 s9, s1, 0
	s_add_u32 s10, s0, 0x1200000
	s_addc_u32 s11, s1, 0
	s_add_u32 s12, s0, 0x1000000
	s_addc_u32 s13, s1, 0
	s_add_u32 s14, s0, 0xf00000
	s_addc_u32 s15, s1, 0
	s_add_u32 s16, s0, 0xd00000
	s_addc_u32 s17, s1, 0
	s_add_u32 s18, s0, 0xb00000
	v_and_b32_e32 v4, 31, v1
	v_lshlrev_b32_e32 v5, 1, v1
	s_addc_u32 s19, s1, 0
	v_ashrrev_i32_e32 v3, 6, v1
	v_and_or_b32 v6, v5, 64, v4
	v_lshlrev_b32_e32 v4, 2, v2
	s_movk_i32 s3, 0x104
	s_add_u32 s20, s0, 0x900000
	v_lshl_or_b32 v7, v2, 8, v4
	v_mul_lo_u32 v15, v3, s3
	s_addc_u32 s21, s1, 0
	v_mov_b32_e32 v5, 0
	v_lshl_add_u32 v7, v3, 2, v7
	v_add_u32_e32 v8, 8, v3
	v_add_u32_e32 v9, 16, v3
	v_add_u32_e32 v10, 24, v3
	v_add_u32_e32 v11, 32, v3
	v_add_u32_e32 v12, 40, v3
	v_add_u32_e32 v13, 48, v3
	v_add_u32_e32 v14, 56, v3
	s_movk_i32 s3, 0x400
	v_add_u32_e32 v15, v4, v15
	v_lshlrev_b32_e32 v4, 1, v2
	s_movk_i32 s33, 0x7fff
	s_mov_b32 s36, s2
	s_branch .LBB0_4
